# normmod3: shift/scale loads before the next-row prefetch, counted vmcnt(8), next-row wait at first use (all three normmod loops now)
# baseline (speedup 1.0000x reference)
; __device__ __forceinline__ void phase_normmod(const float* src, const float* gain, const float* ada, int shoff, int scoff, bf16_t* dst) {
;     ...
;     for (int m = gw; m < M_; m += NGW) {
;         const int mn = (m + NGW < M_) ? m + NGW : m;
;         const float* ab = ada + (size_t)(m >> 12) * NADA;
;         f32x4 vn[8], sh[8], sc[8];
; #pragma unroll
;         for (int j = 0; j < 8; ++j) { const int col = 4 * (lane + 64 * j); sh[j] = *(const f32x4*)(ab + shoff + col); sc[j] = *(const f32x4*)(ab + scoff + col); vn[j] = ((const f32x4*)(src + (size_t)mn * D_) + lane)[64 * j]; }
;         __builtin_amdgcn_sched_barrier(0);
;         float ss = 0.f;
; #pragma unroll
;         for (int j = 0; j < 8; ++j) ss += (v[j][0] * v[j][0] + v[j][1] * v[j][1]) + (v[j][2] * v[j][2] + v[j][3] * v[j][3]);
;         ss = wave_sum(ss);
;         const float rstd = rsqrtf(ss * (1.0f / D_) + 1e-6f);
.LBB0_1088:
	v_add_u32_e32 v221, s68, v128
	v_ashrrev_i32_e32 v65, 12, v128
	v_cmp_gt_i32_e32 vcc, s2, v221
	v_mul_hi_i32_i24_e32 v67, 0x12000, v65
	v_mul_i32_i24_e32 v66, 0x12000, v65
	v_cndmask_b32_e32 v64, v128, v221, vcc
	v_lshl_add_u64 v[66:67], s[34:35], 0, v[66:67]
	s_mov_b64 s[6:7], 0xc000
	v_lshl_add_u64 v[96:97], v[66:67], 0, s[6:7]
	s_mov_b64 s[6:7], 0xe000
	v_ashrrev_i32_e32 v65, 31, v64
	v_lshl_add_u64 v[98:99], v[66:67], 0, s[6:7]
	v_lshlrev_b64 v[64:65], 13, v[64:65]
	v_lshl_add_u64 v[84:85], v[142:143], 0, v[64:65]
	v_lshl_add_u64 v[64:65], v[96:97], 0, v[140:141]
	v_lshl_add_u64 v[68:69], v[98:99], 0, v[140:141]
	v_mov_b32_e32 v147, v141
	global_load_dwordx4 v[64:67], v[64:65], off
	s_nop 0
	global_load_dwordx4 v[162:165], v[68:69], off
	v_lshl_add_u64 v[68:69], v[96:97], 0, v[146:147]
	v_lshl_add_u64 v[72:73], v[98:99], 0, v[146:147]
	v_mov_b32_e32 v149, v141
	global_load_dwordx4 v[68:71], v[68:69], off
	s_nop 0
	global_load_dwordx4 v[166:169], v[72:73], off
	v_lshl_add_u64 v[72:73], v[96:97], 0, v[148:149]
	v_lshl_add_u64 v[76:77], v[98:99], 0, v[148:149]
	v_mov_b32_e32 v151, v141
	global_load_dwordx4 v[72:75], v[72:73], off
	s_nop 0
	global_load_dwordx4 v[170:173], v[76:77], off
	v_lshl_add_u64 v[76:77], v[96:97], 0, v[150:151]
	v_lshl_add_u64 v[80:81], v[98:99], 0, v[150:151]
	v_mov_b32_e32 v153, v141
	v_add_co_u32_e32 v124, vcc, s3, v84
	v_mov_b32_e32 v155, v141
	global_load_dwordx4 v[76:79], v[76:77], off
	s_nop 0
	global_load_dwordx4 v[174:177], v[80:81], off
	v_lshl_add_u64 v[80:81], v[96:97], 0, v[152:153]
	v_lshl_add_u64 v[86:87], v[98:99], 0, v[152:153]
	v_addc_co_u32_e32 v125, vcc, 0, v85, vcc
	v_lshl_add_u64 v[84:85], v[96:97], 0, v[154:155]
	v_lshl_add_u64 v[88:89], v[98:99], 0, v[154:155]
	v_mov_b32_e32 v157, v141
	global_load_dwordx4 v[80:83], v[80:81], off
	s_nop 0
	global_load_dwordx4 v[216:219], v[86:87], off
	s_nop 0
	global_load_dwordx4 v[84:87], v[84:85], off
	s_nop 0
	global_load_dwordx4 v[136:139], v[88:89], off
	v_lshl_add_u64 v[88:89], v[96:97], 0, v[156:157]
	v_lshl_add_u64 v[120:121], v[98:99], 0, v[156:157]
	v_mov_b32_e32 v159, v141
	global_load_dwordx4 v[88:91], v[88:89], off
	s_nop 0
	global_load_dwordx4 v[132:135], v[120:121], off
	v_lshl_add_u64 v[96:97], v[96:97], 0, v[158:159]
	v_lshl_add_u64 v[120:121], v[98:99], 0, v[158:159]
	global_load_dwordx4 v[96:99], v[96:97], off
	s_nop 0
	global_load_dwordx4 v[128:131], v[120:121], off
	s_nop 0
	s_nop 0
	s_movk_i32 s6, 0x3fff
	global_load_dwordx4 v[100:103], v[124:125], off offset:-4096
	global_load_dwordx4 v[92:95], v[124:125], off offset:-3072
	global_load_dwordx4 v[108:111], v[124:125], off offset:-2048
	global_load_dwordx4 v[104:107], v[124:125], off offset:-1024
	global_load_dwordx4 v[116:119], v[124:125], off
	global_load_dwordx4 v[112:115], v[124:125], off offset:1024
	global_load_dwordx4 v[120:123], v[124:125], off offset:2048
	global_load_dwordx4 v[124:127], v[124:125], off offset:3072
	v_cmp_lt_i32_e32 vcc, s6, v221
	v_pk_mul_f32 v[196:197], v[38:39], v[38:39]
	v_pk_mul_f32 v[194:195], v[42:43], v[42:43]
	v_pk_mul_f32 v[200:201], v[36:37], v[36:37]
	v_pk_mul_f32 v[198:199], v[40:41], v[40:41]
	s_waitcnt vmcnt(8)
	v_pk_mul_f32 v[192:193], v[46:47], v[46:47]
	v_pk_mul_f32 v[190:191], v[44:45], v[44:45]
	v_pk_add_f32 v[178:179], v[216:217], 1.0 op_sel_hi:[1,0]
	v_mov_b32_e32 v216, v200
	v_mov_b32_e32 v217, v198
	v_mov_b32_e32 v198, v201
	v_mov_b32_e32 v200, v196
	v_mov_b32_e32 v201, v194
	v_mov_b32_e32 v194, v197
	v_pk_mov_b32 v[196:197], v[190:191], v[192:193] op_sel:[1,0]
	v_mov_b32_e32 v191, v193
	v_pk_add_f32 v[198:199], v[216:217], v[198:199]
	v_pk_add_f32 v[194:195], v[200:201], v[194:195]
	v_mul_f32_e32 v202, v48, v48
	v_mul_f32_e32 v204, v50, v50
	v_pk_add_f32 v[190:191], v[196:197], v[190:191]
	v_pk_add_f32 v[194:195], v[198:199], v[194:195]
	v_pk_add_f32 v[160:161], v[164:165], 1.0 op_sel_hi:[1,0]
	v_pk_add_f32 v[164:165], v[168:169], 1.0 op_sel_hi:[1,0]
	v_pk_add_f32 v[168:169], v[172:173], 1.0 op_sel_hi:[1,0]
	v_pk_add_f32 v[172:173], v[176:177], 1.0 op_sel_hi:[1,0]
	v_pk_add_f32 v[176:177], v[218:219], 1.0 op_sel_hi:[1,0]
	v_pk_fma_f32 v[192:193], v[48:49], v[48:49], v[202:203] op_sel_hi:[1,1,0]
	v_pk_fma_f32 v[218:219], v[50:51], v[50:51], v[204:205] op_sel_hi:[1,1,0]
	v_pk_add_f32 v[190:191], v[190:191], v[190:191] op_sel_hi:[0,1]
	v_pk_add_f32 v[194:195], v[194:195], v[194:195] op_sel_hi:[0,1]
	v_pk_mul_f32 v[182:183], v[62:63], v[62:63]
	v_pk_mul_f32 v[180:181], v[60:61], v[60:61]
	v_mul_f32_e32 v192, v52, v52
	v_mul_f32_e32 v218, v53, v53
	v_mul_f32_e32 v190, v54, v54
	v_mul_f32_e32 v194, v55, v55
	v_pk_mov_b32 v[222:223], v[180:181], v[182:183] op_sel:[1,0]
	v_mov_b32_e32 v181, v183
	v_pk_add_f32 v[192:193], v[192:193], v[218:219]
	v_pk_add_f32 v[190:191], v[190:191], v[194:195]
	v_mul_f32_e32 v206, v56, v56
	v_mul_f32_e32 v220, v58, v58
	v_pk_add_f32 v[180:181], v[222:223], v[180:181]
	v_pk_add_f32 v[190:191], v[192:193], v[190:191]
	v_pk_add_f32 v[188:189], v[128:129], 1.0 op_sel_hi:[1,0]
	v_mov_b32_e32 v128, v221
	v_pk_fma_f32 v[182:183], v[56:57], v[56:57], v[206:207] op_sel_hi:[1,1,0]
	v_pk_fma_f32 v[220:221], v[58:59], v[58:59], v[220:221] op_sel_hi:[1,1,0]
	v_pk_add_f32 v[180:181], v[180:181], v[180:181] op_sel_hi:[0,1]
	v_pk_add_f32 v[190:191], v[190:191], v[190:191] op_sel_hi:[0,1]
	v_mul_f32_e32 v182, v212, v212
	v_mul_f32_e32 v220, v213, v213
	v_mul_f32_e32 v180, v214, v214
	v_mul_f32_e32 v190, v215, v215
	v_pk_add_f32 v[182:183], v[182:183], v[220:221]
	v_pk_add_f32 v[180:181], v[180:181], v[190:191]
	s_mov_b32 s6, 0x800000
	v_pk_add_f32 v[180:181], v[182:183], v[180:181]
	s_or_b64 s[8:9], vcc, s[8:9]
	v_add_f32_e32 v129, v180, v181
	ds_bpermute_b32 v147, v203, v129
	v_pk_add_f32 v[162:163], v[162:163], 1.0 op_sel_hi:[1,0]
	v_pk_add_f32 v[166:167], v[166:167], 1.0 op_sel_hi:[1,0]
	v_pk_add_f32 v[170:171], v[170:171], 1.0 op_sel_hi:[1,0]
	v_pk_add_f32 v[174:175], v[174:175], 1.0 op_sel_hi:[1,0]
	s_waitcnt lgkmcnt(0)
; __device__ __forceinline__ unsigned cvt_pk_bf16(float lo, float hi) { f32x2v v = {lo, hi}; bf16x2_t r = __builtin_convertvector(v, bf16x2_t); return __builtin_bit_cast(unsigned, r); }
; __device__ __forceinline__ void phase_normmod(const float* src, const float* gain, const float* ada, int shoff, int scoff, bf16_t* dst) {
;     ...
;         ss = wave_sum(ss);
;         const float rstd = rsqrtf(ss * (1.0f / D_) + 1e-6f);
; #pragma unroll
;         for (int j = 0; j < 8; ++j) { const int col = 4 * (lane + 64 * j);
;             const f32x4 y = v[j] * rstd * g[j] * (sc[j] + 1.0f) + sh[j];
;             u32x2 w; w.x = cvt_pk_bf16(y[0], y[1]); w.y = cvt_pk_bf16(y[2], y[3]);
;             *(u32x2*)(dst + (size_t)m * D_ + col) = w; }
; #pragma unroll
;         for (int j = 0; j < 8; ++j) v[j] = vn[j];
	v_add_f32_e32 v129, v129, v147
	ds_bpermute_b32 v147, v205, v129
	v_pk_add_f32 v[138:139], v[138:139], 1.0 op_sel_hi:[1,0]
	v_pk_add_f32 v[136:137], v[136:137], 1.0 op_sel_hi:[1,0]
	v_pk_add_f32 v[134:135], v[134:135], 1.0 op_sel_hi:[1,0]
	v_pk_add_f32 v[132:133], v[132:133], 1.0 op_sel_hi:[1,0]
	s_waitcnt lgkmcnt(0)
	v_add_f32_e32 v129, v129, v147
	ds_bpermute_b32 v147, v207, v129
	v_pk_add_f32 v[130:131], v[130:131], 1.0 op_sel_hi:[1,0]
	s_waitcnt lgkmcnt(0)
	v_add_f32_e32 v129, v129, v147
	ds_bpermute_b32 v147, v208, v129
	s_waitcnt lgkmcnt(0)
	v_add_f32_e32 v129, v129, v147
	ds_bpermute_b32 v147, v209, v129
	s_waitcnt lgkmcnt(0)
	v_add_f32_e32 v129, v129, v147
	ds_bpermute_b32 v147, v210, v129
	s_waitcnt lgkmcnt(0)
	v_add_f32_e32 v129, v129, v147
	v_fmamk_f32 v129, v129, 0x3a000000, v211
	v_mul_f32_e32 v147, 0x4b800000, v129
	v_cmp_gt_f32_e32 vcc, s6, v129
	s_nop 1
	v_cndmask_b32_e32 v129, v129, v147, vcc
	v_rsq_f32_e32 v129, v129
	s_nop 0
	v_mul_f32_e32 v147, 0x45800000, v129
	v_cndmask_b32_e32 v180, v129, v147, vcc
	v_pk_mul_f32 v[182:183], v[38:39], v[180:181] op_sel_hi:[1,0]
	v_pk_mul_f32 v[190:191], v[36:37], v[180:181] op_sel_hi:[1,0]
	v_pk_mul_f32 v[192:193], v[42:43], v[180:181] op_sel_hi:[1,0]
	v_pk_mul_f32 v[194:195], v[40:41], v[180:181] op_sel_hi:[1,0]
	v_pk_mul_f32 v[196:197], v[46:47], v[180:181] op_sel_hi:[1,0]
	v_pk_mul_f32 v[198:199], v[44:45], v[180:181] op_sel_hi:[1,0]
	v_pk_mul_f32 v[200:201], v[50:51], v[180:181] op_sel_hi:[1,0]
	v_pk_mul_f32 v[216:217], v[48:49], v[180:181] op_sel_hi:[1,0]
	v_pk_mul_f32 v[218:219], v[54:55], v[180:181] op_sel_hi:[1,0]
	v_pk_mul_f32 v[220:221], v[52:53], v[180:181] op_sel_hi:[1,0]
	v_pk_mul_f32 v[222:223], v[62:63], v[180:181] op_sel_hi:[1,0]
	v_pk_mul_f32 v[224:225], v[60:61], v[180:181] op_sel_hi:[1,0]
	v_pk_mul_f32 v[226:227], v[58:59], v[180:181] op_sel_hi:[1,0]
	v_pk_mul_f32 v[228:229], v[56:57], v[180:181] op_sel_hi:[1,0]
	v_pk_mul_f32 v[230:231], v[34:35], v[180:181] op_sel_hi:[1,0]
	v_pk_mul_f32 v[180:181], v[32:33], v[180:181] op_sel_hi:[1,0]
	s_waitcnt vmcnt(0)
	v_mov_b32_e32 v212, v124
	v_mov_b32_e32 v213, v125
	v_mov_b32_e32 v214, v126
	v_mov_b32_e32 v215, v127
	v_mov_b64_e32 v[32:33], v[124:125]
	v_mov_b32_e32 v40, v92
	v_mov_b32_e32 v41, v93
	v_mov_b32_e32 v42, v94
	v_mov_b32_e32 v43, v95
	v_pk_mul_f32 v[92:93], v[0:1], v[190:191]
	v_pk_mul_f32 v[94:95], v[2:3], v[182:183]
	v_mov_b64_e32 v[34:35], v[126:127]
	v_mov_b32_e32 v36, v100
	v_mov_b32_e32 v37, v101
	v_mov_b32_e32 v38, v102
	v_mov_b32_e32 v39, v103
	v_mov_b32_e32 v44, v108
	v_mov_b32_e32 v45, v109
	v_mov_b32_e32 v46, v110
	v_mov_b32_e32 v47, v111
	v_mov_b32_e32 v48, v104
	v_mov_b32_e32 v49, v105
	v_mov_b32_e32 v50, v106
	v_mov_b32_e32 v51, v107
	v_mov_b32_e32 v52, v116
	v_mov_b32_e32 v53, v117
	v_mov_b32_e32 v54, v118
	v_mov_b32_e32 v55, v119
	v_mov_b32_e32 v60, v112
	v_mov_b32_e32 v61, v113
	v_mov_b32_e32 v62, v114
	v_mov_b32_e32 v63, v115
	v_mov_b32_e32 v56, v120
	v_mov_b32_e32 v57, v121
	v_mov_b32_e32 v58, v122
	v_mov_b32_e32 v59, v123
	v_pk_mul_f32 v[100:101], v[4:5], v[194:195]
	v_pk_mul_f32 v[102:103], v[6:7], v[192:193]
	v_pk_mul_f32 v[104:105], v[8:9], v[198:199]
	v_pk_mul_f32 v[106:107], v[10:11], v[196:197]
	v_pk_mul_f32 v[108:109], v[12:13], v[216:217]
	v_pk_mul_f32 v[110:111], v[14:15], v[200:201]
	v_pk_mul_f32 v[112:113], v[16:17], v[220:221]
	v_pk_mul_f32 v[114:115], v[18:19], v[218:219]
	v_pk_mul_f32 v[116:117], v[20:21], v[224:225]
	v_pk_mul_f32 v[118:119], v[22:23], v[222:223]
	v_pk_mul_f32 v[120:121], v[24:25], v[228:229]
	v_pk_mul_f32 v[122:123], v[26:27], v[226:227]
	v_pk_mul_f32 v[124:125], v[28:29], v[180:181]
	v_pk_mul_f32 v[126:127], v[30:31], v[230:231]
	v_pk_fma_f32 v[66:67], v[160:161], v[94:95], v[66:67]
	v_pk_fma_f32 v[64:65], v[162:163], v[92:93], v[64:65]
	v_pk_fma_f32 v[70:71], v[164:165], v[102:103], v[70:71]
	v_pk_fma_f32 v[68:69], v[166:167], v[100:101], v[68:69]
	v_pk_fma_f32 v[74:75], v[168:169], v[106:107], v[74:75]
	v_pk_fma_f32 v[72:73], v[170:171], v[104:105], v[72:73]
	v_pk_fma_f32 v[78:79], v[172:173], v[110:111], v[78:79]
	v_pk_fma_f32 v[76:77], v[174:175], v[108:109], v[76:77]
	v_pk_fma_f32 v[82:83], v[176:177], v[114:115], v[82:83]
	v_pk_fma_f32 v[80:81], v[178:179], v[112:113], v[80:81]
	v_pk_fma_f32 v[86:87], v[138:139], v[118:119], v[86:87]
	v_pk_fma_f32 v[84:85], v[136:137], v[116:117], v[84:85]
	v_pk_fma_f32 v[90:91], v[134:135], v[122:123], v[90:91]
	v_pk_fma_f32 v[88:89], v[132:133], v[120:121], v[88:89]
	v_pk_fma_f32 v[92:93], v[130:131], v[126:127], v[98:99]
	v_pk_fma_f32 v[94:95], v[188:189], v[124:125], v[96:97]
	v_cvt_pk_bf16_f32 v64, v64, v65
	v_cvt_pk_bf16_f32 v65, v66, v67
	v_cvt_pk_bf16_f32 v66, v68, v69
	v_cvt_pk_bf16_f32 v67, v70, v71
	v_cvt_pk_bf16_f32 v68, v72, v73
	v_cvt_pk_bf16_f32 v69, v74, v75
	v_cvt_pk_bf16_f32 v70, v76, v77
	v_cvt_pk_bf16_f32 v71, v78, v79
	v_cvt_pk_bf16_f32 v72, v80, v81
	v_cvt_pk_bf16_f32 v73, v82, v83
	v_cvt_pk_bf16_f32 v74, v84, v85
	v_cvt_pk_bf16_f32 v75, v86, v87
	v_cvt_pk_bf16_f32 v76, v88, v89
	v_cvt_pk_bf16_f32 v77, v90, v91
	v_cvt_pk_bf16_f32 v78, v94, v95
	v_cvt_pk_bf16_f32 v79, v92, v93
	global_store_dwordx2 v[144:145], v[64:65], off
	global_store_dwordx2 v[144:145], v[66:67], off offset:512
	global_store_dwordx2 v[144:145], v[68:69], off offset:1024
	global_store_dwordx2 v[144:145], v[70:71], off offset:1536
	global_store_dwordx2 v[144:145], v[72:73], off offset:2048
	global_store_dwordx2 v[144:145], v[74:75], off offset:2560
	global_store_dwordx2 v[144:145], v[76:77], off offset:3072
	global_store_dwordx2 v[144:145], v[78:79], off offset:3584
	v_lshl_add_u64 v[144:145], v[144:145], 0, s[4:5]
	s_andn2_b64 exec, exec, s[8:9]
	s_cbranch_execnz .LBB0_1088
